# v19 plus batched MODE1 epilogue (x += coef*g*acc with 8 loads in flight, g loaded once per tile)
# speedup vs baseline: 1.0082x; 1.0082x over previous
;     __device__ __forceinline__ void operator()(const f32x4 (&acc)[2][2][4][2], const Unit& u, int wr, int wc, int fr, int fq) const {
;     ...
;                     } else if (MODE == 1) {
;                         const int b = r >> 12;
; #pragma unroll
;                         for (int n = 0; n < 2; ++n) { const int c = cb + 16 * n + 4 * fq; const f32x4 g = *(const f32x4*)(gv + b * 9216 + c); f32x4* xp = (f32x4*)(F + (size_t)r * 1024 + c);
;                             f32x4 x = *xp; x += (n == 0 ? v0 : v1) * g * coef; *xp = x; }
.Lepi0_skip:
	s_cmp_eq_u32 s66, 1
	s_cbranch_scc0 .Lepi1_skip
	v_or_b32_e32 v144, s86, v132
	v_mov_b32_e32 v145, 0
	s_lshl_b64 s[90:91], s[88:89], 2
	s_add_u32 s90, s76, s90
	s_addc_u32 s91, s77, s91
	v_lshl_add_u64 v[142:143], s[72:73], 0, v[140:141]
	v_lshl_add_u64 v[196:197], v[144:145], 2, s[90:91]
	v_lshl_add_u64 v[138:139], v[144:145], 2, v[142:143]
	s_mov_b32 s4, 0x10000
	s_mov_b32 s5, 0
	s_mov_b32 s28, 0x50000
	s_mov_b32 s29, 0
	global_load_dwordx4 v[220:223], v[196:197], off
	global_load_dwordx4 v[224:227], v[196:197], off offset:64
	global_load_dwordx4 v[228:231], v[196:197], off offset:512
	global_load_dwordx4 v[232:235], v[196:197], off offset:576
	v_lshl_add_u64 v[140:141], v[138:139], 0, s[4:5]
	global_load_dwordx4 v[160:163], v[138:139], off
	global_load_dwordx4 v[164:167], v[138:139], off offset:64
	global_load_dwordx4 v[168:171], v[138:139], off offset:512
	global_load_dwordx4 v[176:179], v[138:139], off offset:576
	global_load_dwordx4 v[180:183], v[140:141], off
	global_load_dwordx4 v[184:187], v[140:141], off offset:64
	global_load_dwordx4 v[188:191], v[140:141], off offset:512
	global_load_dwordx4 v[192:195], v[140:141], off offset:576
	v_lshl_add_u64 v[142:143], v[140:141], 0, s[4:5]
	v_lshl_add_u64 v[144:145], v[142:143], 0, s[4:5]
	v_lshl_add_u64 v[172:173], v[144:145], 0, s[28:29]
	s_waitcnt vmcnt(8)
	v_pk_mul_f32 v[124:125], v[124:125], v[220:221]
	v_pk_mul_f32 v[126:127], v[126:127], v[222:223]
	v_pk_mul_f32 v[120:121], v[120:121], v[224:225]
	v_pk_mul_f32 v[122:123], v[122:123], v[226:227]
	v_pk_mul_f32 v[116:117], v[116:117], v[228:229]
	v_pk_mul_f32 v[118:119], v[118:119], v[230:231]
	v_pk_mul_f32 v[112:113], v[112:113], v[232:233]
	v_pk_mul_f32 v[114:115], v[114:115], v[234:235]
	v_pk_mul_f32 v[108:109], v[108:109], v[220:221]
	v_pk_mul_f32 v[110:111], v[110:111], v[222:223]
	v_pk_mul_f32 v[104:105], v[104:105], v[224:225]
	v_pk_mul_f32 v[106:107], v[106:107], v[226:227]
	v_pk_mul_f32 v[100:101], v[100:101], v[228:229]
	v_pk_mul_f32 v[102:103], v[102:103], v[230:231]
	v_pk_mul_f32 v[96:97], v[96:97], v[232:233]
	v_pk_mul_f32 v[98:99], v[98:99], v[234:235]
	v_pk_mul_f32 v[92:93], v[92:93], v[220:221]
	v_pk_mul_f32 v[94:95], v[94:95], v[222:223]
	v_pk_mul_f32 v[88:89], v[88:89], v[224:225]
	v_pk_mul_f32 v[90:91], v[90:91], v[226:227]
	v_pk_mul_f32 v[84:85], v[84:85], v[228:229]
	v_pk_mul_f32 v[86:87], v[86:87], v[230:231]
	v_pk_mul_f32 v[80:81], v[80:81], v[232:233]
	v_pk_mul_f32 v[82:83], v[82:83], v[234:235]
	v_pk_mul_f32 v[76:77], v[76:77], v[220:221]
	v_pk_mul_f32 v[78:79], v[78:79], v[222:223]
	v_pk_mul_f32 v[72:73], v[72:73], v[224:225]
	v_pk_mul_f32 v[74:75], v[74:75], v[226:227]
	v_pk_mul_f32 v[68:69], v[68:69], v[228:229]
	v_pk_mul_f32 v[70:71], v[70:71], v[230:231]
	v_pk_mul_f32 v[64:65], v[64:65], v[232:233]
	v_pk_mul_f32 v[66:67], v[66:67], v[234:235]
	v_pk_mul_f32 v[60:61], v[60:61], v[220:221]
	v_pk_mul_f32 v[62:63], v[62:63], v[222:223]
	v_pk_mul_f32 v[56:57], v[56:57], v[224:225]
	v_pk_mul_f32 v[58:59], v[58:59], v[226:227]
	v_pk_mul_f32 v[52:53], v[52:53], v[228:229]
	v_pk_mul_f32 v[54:55], v[54:55], v[230:231]
	v_pk_mul_f32 v[48:49], v[48:49], v[232:233]
	v_pk_mul_f32 v[50:51], v[50:51], v[234:235]
	v_pk_mul_f32 v[44:45], v[44:45], v[220:221]
	v_pk_mul_f32 v[46:47], v[46:47], v[222:223]
	v_pk_mul_f32 v[40:41], v[40:41], v[224:225]
	v_pk_mul_f32 v[42:43], v[42:43], v[226:227]
	v_pk_mul_f32 v[36:37], v[36:37], v[228:229]
	v_pk_mul_f32 v[38:39], v[38:39], v[230:231]
	v_pk_mul_f32 v[32:33], v[32:33], v[232:233]
	v_pk_mul_f32 v[34:35], v[34:35], v[234:235]
	v_pk_mul_f32 v[28:29], v[28:29], v[220:221]
	v_pk_mul_f32 v[30:31], v[30:31], v[222:223]
	v_pk_mul_f32 v[24:25], v[24:25], v[224:225]
	v_pk_mul_f32 v[26:27], v[26:27], v[226:227]
	v_pk_mul_f32 v[20:21], v[20:21], v[228:229]
	v_pk_mul_f32 v[22:23], v[22:23], v[230:231]
	v_pk_mul_f32 v[16:17], v[16:17], v[232:233]
	v_pk_mul_f32 v[18:19], v[18:19], v[234:235]
	v_pk_mul_f32 v[12:13], v[12:13], v[220:221]
	v_pk_mul_f32 v[14:15], v[14:15], v[222:223]
	v_pk_mul_f32 v[8:9], v[8:9], v[224:225]
	v_pk_mul_f32 v[10:11], v[10:11], v[226:227]
	v_pk_mul_f32 v[4:5], v[4:5], v[228:229]
	v_pk_mul_f32 v[6:7], v[6:7], v[230:231]
	v_pk_mul_f32 v[0:1], v[0:1], v[232:233]
	v_pk_mul_f32 v[2:3], v[2:3], v[234:235]
	v_lshl_add_u64 v[196:197], v[172:173], 0, s[4:5]
	global_load_dwordx4 v[220:223], v[142:143], off
	global_load_dwordx4 v[224:227], v[142:143], off offset:64
	global_load_dwordx4 v[228:231], v[142:143], off offset:512
	global_load_dwordx4 v[232:235], v[142:143], off offset:576
	global_load_dwordx4 v[236:239], v[144:145], off
	global_load_dwordx4 v[240:243], v[144:145], off offset:64
	global_load_dwordx4 v[244:247], v[144:145], off offset:512
	global_load_dwordx4 v[248:251], v[144:145], off offset:576
	s_waitcnt vmcnt(8)
;     __device__ __forceinline__ void operator()(const f32x4 (&acc)[2][2][4][2], const Unit& u, int wr, int wc, int fr, int fq) const {
;     ...
;                     } else if (MODE == 1) {
;                         const int b = r >> 12;
; #pragma unroll
;                         for (int n = 0; n < 2; ++n) { const int c = cb + 16 * n + 4 * fq; const f32x4 g = *(const f32x4*)(gv + b * 9216 + c); f32x4* xp = (f32x4*)(F + (size_t)r * 1024 + c);
;                             f32x4 x = *xp; x += (n == 0 ? v0 : v1) * g * coef; *xp = x; }
	v_pk_fma_f32 v[124:125], s[78:79], v[124:125], v[160:161]
	v_pk_fma_f32 v[126:127], s[78:79], v[126:127], v[162:163]
	v_pk_fma_f32 v[120:121], s[78:79], v[120:121], v[164:165]
	v_pk_fma_f32 v[122:123], s[78:79], v[122:123], v[166:167]
	v_pk_fma_f32 v[116:117], s[78:79], v[116:117], v[168:169]
	v_pk_fma_f32 v[118:119], s[78:79], v[118:119], v[170:171]
	v_pk_fma_f32 v[112:113], s[78:79], v[112:113], v[176:177]
	v_pk_fma_f32 v[114:115], s[78:79], v[114:115], v[178:179]
	v_pk_fma_f32 v[108:109], s[78:79], v[108:109], v[180:181]
	v_pk_fma_f32 v[110:111], s[78:79], v[110:111], v[182:183]
	v_pk_fma_f32 v[104:105], s[78:79], v[104:105], v[184:185]
	v_pk_fma_f32 v[106:107], s[78:79], v[106:107], v[186:187]
	v_pk_fma_f32 v[100:101], s[78:79], v[100:101], v[188:189]
	v_pk_fma_f32 v[102:103], s[78:79], v[102:103], v[190:191]
	v_pk_fma_f32 v[96:97], s[78:79], v[96:97], v[192:193]
	v_pk_fma_f32 v[98:99], s[78:79], v[98:99], v[194:195]
	global_store_dwordx4 v[138:139], v[124:127], off
	global_store_dwordx4 v[138:139], v[120:123], off offset:64
	global_store_dwordx4 v[138:139], v[116:119], off offset:512
	global_store_dwordx4 v[138:139], v[112:115], off offset:576
	global_store_dwordx4 v[140:141], v[108:111], off
	global_store_dwordx4 v[140:141], v[104:107], off offset:64
	global_store_dwordx4 v[140:141], v[100:103], off offset:512
	global_store_dwordx4 v[140:141], v[96:99], off offset:576
	global_load_dwordx4 v[160:163], v[172:173], off
	global_load_dwordx4 v[164:167], v[172:173], off offset:64
	global_load_dwordx4 v[168:171], v[172:173], off offset:512
	global_load_dwordx4 v[176:179], v[172:173], off offset:576
	global_load_dwordx4 v[180:183], v[196:197], off
	global_load_dwordx4 v[184:187], v[196:197], off offset:64
	global_load_dwordx4 v[188:191], v[196:197], off offset:512
	global_load_dwordx4 v[192:195], v[196:197], off offset:576
	s_waitcnt vmcnt(8)
	v_pk_fma_f32 v[92:93], s[78:79], v[92:93], v[220:221]
	v_pk_fma_f32 v[94:95], s[78:79], v[94:95], v[222:223]
	v_pk_fma_f32 v[88:89], s[78:79], v[88:89], v[224:225]
	v_pk_fma_f32 v[90:91], s[78:79], v[90:91], v[226:227]
	v_pk_fma_f32 v[84:85], s[78:79], v[84:85], v[228:229]
	v_pk_fma_f32 v[86:87], s[78:79], v[86:87], v[230:231]
	v_pk_fma_f32 v[80:81], s[78:79], v[80:81], v[232:233]
	v_pk_fma_f32 v[82:83], s[78:79], v[82:83], v[234:235]
	v_pk_fma_f32 v[76:77], s[78:79], v[76:77], v[236:237]
	v_pk_fma_f32 v[78:79], s[78:79], v[78:79], v[238:239]
	v_pk_fma_f32 v[72:73], s[78:79], v[72:73], v[240:241]
	v_pk_fma_f32 v[74:75], s[78:79], v[74:75], v[242:243]
	v_pk_fma_f32 v[68:69], s[78:79], v[68:69], v[244:245]
	v_pk_fma_f32 v[70:71], s[78:79], v[70:71], v[246:247]
	v_pk_fma_f32 v[64:65], s[78:79], v[64:65], v[248:249]
	v_pk_fma_f32 v[66:67], s[78:79], v[66:67], v[250:251]
	global_store_dwordx4 v[142:143], v[92:95], off
	global_store_dwordx4 v[142:143], v[88:91], off offset:64
	global_store_dwordx4 v[142:143], v[84:87], off offset:512
	global_store_dwordx4 v[142:143], v[80:83], off offset:576
	global_store_dwordx4 v[144:145], v[76:79], off
	global_store_dwordx4 v[144:145], v[72:75], off offset:64
	global_store_dwordx4 v[144:145], v[68:71], off offset:512
	global_store_dwordx4 v[144:145], v[64:67], off offset:576
	s_nop 1
	v_lshl_add_u64 v[138:139], v[196:197], 0, s[4:5]
	v_lshl_add_u64 v[140:141], v[138:139], 0, s[4:5]
	global_load_dwordx4 v[220:223], v[138:139], off
	global_load_dwordx4 v[224:227], v[138:139], off offset:64
	global_load_dwordx4 v[228:231], v[138:139], off offset:512
	global_load_dwordx4 v[232:235], v[138:139], off offset:576
	global_load_dwordx4 v[236:239], v[140:141], off
	global_load_dwordx4 v[240:243], v[140:141], off offset:64
	global_load_dwordx4 v[244:247], v[140:141], off offset:512
	global_load_dwordx4 v[248:251], v[140:141], off offset:576
	s_waitcnt vmcnt(8)
	v_pk_fma_f32 v[60:61], s[78:79], v[60:61], v[160:161]
	v_pk_fma_f32 v[62:63], s[78:79], v[62:63], v[162:163]
	v_pk_fma_f32 v[56:57], s[78:79], v[56:57], v[164:165]
	v_pk_fma_f32 v[58:59], s[78:79], v[58:59], v[166:167]
	v_pk_fma_f32 v[52:53], s[78:79], v[52:53], v[168:169]
	v_pk_fma_f32 v[54:55], s[78:79], v[54:55], v[170:171]
	v_pk_fma_f32 v[48:49], s[78:79], v[48:49], v[176:177]
	v_pk_fma_f32 v[50:51], s[78:79], v[50:51], v[178:179]
	v_pk_fma_f32 v[44:45], s[78:79], v[44:45], v[180:181]
	v_pk_fma_f32 v[46:47], s[78:79], v[46:47], v[182:183]
	v_pk_fma_f32 v[40:41], s[78:79], v[40:41], v[184:185]
	v_pk_fma_f32 v[42:43], s[78:79], v[42:43], v[186:187]
	v_pk_fma_f32 v[36:37], s[78:79], v[36:37], v[188:189]
	v_pk_fma_f32 v[38:39], s[78:79], v[38:39], v[190:191]
	v_pk_fma_f32 v[32:33], s[78:79], v[32:33], v[192:193]
	v_pk_fma_f32 v[34:35], s[78:79], v[34:35], v[194:195]
	s_waitcnt vmcnt(0)
	v_pk_fma_f32 v[28:29], s[78:79], v[28:29], v[220:221]
	v_pk_fma_f32 v[30:31], s[78:79], v[30:31], v[222:223]
	v_pk_fma_f32 v[24:25], s[78:79], v[24:25], v[224:225]
	v_pk_fma_f32 v[26:27], s[78:79], v[26:27], v[226:227]
	v_pk_fma_f32 v[20:21], s[78:79], v[20:21], v[228:229]
	v_pk_fma_f32 v[22:23], s[78:79], v[22:23], v[230:231]
	v_pk_fma_f32 v[16:17], s[78:79], v[16:17], v[232:233]
	v_pk_fma_f32 v[18:19], s[78:79], v[18:19], v[234:235]
	v_pk_fma_f32 v[12:13], s[78:79], v[12:13], v[236:237]
	v_pk_fma_f32 v[14:15], s[78:79], v[14:15], v[238:239]
	v_pk_fma_f32 v[8:9], s[78:79], v[8:9], v[240:241]
	v_pk_fma_f32 v[10:11], s[78:79], v[10:11], v[242:243]
	v_pk_fma_f32 v[4:5], s[78:79], v[4:5], v[244:245]
	v_pk_fma_f32 v[6:7], s[78:79], v[6:7], v[246:247]
	v_pk_fma_f32 v[0:1], s[78:79], v[0:1], v[248:249]
	v_pk_fma_f32 v[2:3], s[78:79], v[2:3], v[250:251]
	global_store_dwordx4 v[172:173], v[60:63], off
	global_store_dwordx4 v[172:173], v[56:59], off offset:64
	global_store_dwordx4 v[172:173], v[52:55], off offset:512
	global_store_dwordx4 v[172:173], v[48:51], off offset:576
	global_store_dwordx4 v[196:197], v[44:47], off
	global_store_dwordx4 v[196:197], v[40:43], off offset:64
	global_store_dwordx4 v[196:197], v[36:39], off offset:512
	global_store_dwordx4 v[196:197], v[32:35], off offset:576
	global_store_dwordx4 v[138:139], v[28:31], off
	global_store_dwordx4 v[138:139], v[24:27], off offset:64
	global_store_dwordx4 v[138:139], v[20:23], off offset:512
	global_store_dwordx4 v[138:139], v[16:19], off offset:576
	global_store_dwordx4 v[140:141], v[12:15], off
	global_store_dwordx4 v[140:141], v[8:11], off offset:64
	global_store_dwordx4 v[140:141], v[4:7], off offset:512
	global_store_dwordx4 v[140:141], v[0:3], off offset:576
	s_branch .LBB0_562
